# S5 carry step as four fmas (fewer roundings, two-deep chain)
# speedup vs baseline: 1.0017x; 1.0017x over previous
; #define LAS __attribute__((address_space(3)))
; __device__ __forceinline__ f32x2 cmul(f32x2 a, f32x2 b) { return (f32x2){a.x * b.x - a.y * b.y, a.x * b.y + a.y * b.x}; }
; __global__ void __launch_bounds__(512, 2) fwd_kernel(Args a) {
;     ...
;                 const f32x2 aT = AT[g * NP + lane]; f32x2 S = (f32x2){0.f, 0.f};
;                 const int ch = lane >> 1, wo = (lane & 1) * 8;
;                 for (int c = 0; c < c0; c += 16) {
;                     f32x2 ev[16];
; #pragma unroll
;                     for (int q = 0; q < 16; ++q) ev[q] = *(const LAS f32x2*)(EbB + (c + q) * 512 + ((ch ^ q) << 4) + wo);
; #pragma unroll
;                     for (int q = 0; q < 16; ++q) S = cmul(aT, S) + ev[q];
;                 }
.LBB0_281:
	v_add_u32_e32 v28, v10, v84
	v_add_u32_e32 v30, v11, v84
	v_add_u32_e32 v32, v12, v84
	v_add_u32_e32 v36, v13, v84
	v_add_u32_e32 v38, v14, v84
	v_add_u32_e32 v40, v15, v84
	v_add_u32_e32 v42, v16, v84
	v_add_u32_e32 v44, v17, v84
	v_add_u32_e32 v46, v18, v84
	v_add_u32_e32 v48, v19, v84
	v_add_u32_e32 v50, v20, v84
	v_add_u32_e32 v52, v21, v84
	v_add_u32_e32 v54, v22, v84
	v_add_u32_e32 v56, v23, v84
	v_add_u32_e32 v58, v24, v84
	v_add_u32_e32 v60, v25, v84
	ds_read_b64 v[28:29], v28
	ds_read_b64 v[30:31], v30
	ds_read_b64 v[32:33], v32
	ds_read_b64 v[36:37], v36
	ds_read_b64 v[38:39], v38
	ds_read_b64 v[40:41], v40
	ds_read_b64 v[42:43], v42
	ds_read_b64 v[44:45], v44
	ds_read_b64 v[46:47], v46
	ds_read_b64 v[48:49], v48
	ds_read_b64 v[50:51], v50
	ds_read_b64 v[52:53], v52
	ds_read_b64 v[54:55], v54
	ds_read_b64 v[56:57], v56
	ds_read_b64 v[58:59], v58
	ds_read_b64 v[60:61], v60
	s_waitcnt lgkmcnt(14)
	v_fma_f32 v27, -v5, v9, v28
	v_fma_f32 v26, v4, v8, v29
	v_fma_f32 v8, v2, v8, v27
	v_fma_f32 v9, v3, v9, v26
	s_add_i32 s35, s35, 16
	v_add_u32_e32 v25, 0x2000, v25
	v_add_u32_e32 v24, 0x2000, v24
	v_fma_f32 v27, -v5, v9, v30
	v_fma_f32 v26, v4, v8, v31
	v_fma_f32 v8, v2, v8, v27
	v_fma_f32 v9, v3, v9, v26
	v_add_u32_e32 v23, 0x2000, v23
	v_add_u32_e32 v22, 0x2000, v22
	v_add_u32_e32 v21, 0x2000, v21
	s_waitcnt lgkmcnt(13)
	v_fma_f32 v27, -v5, v9, v32
	v_fma_f32 v26, v4, v8, v33
	v_fma_f32 v8, v2, v8, v27
	v_fma_f32 v9, v3, v9, v26
	v_add_u32_e32 v20, 0x2000, v20
	v_add_u32_e32 v19, 0x2000, v19
	v_add_u32_e32 v18, 0x2000, v18
	s_waitcnt lgkmcnt(12)
	v_fma_f32 v27, -v5, v9, v36
	v_fma_f32 v26, v4, v8, v37
	v_fma_f32 v8, v2, v8, v27
	v_fma_f32 v9, v3, v9, v26
	v_add_u32_e32 v17, 0x2000, v17
	v_add_u32_e32 v16, 0x2000, v16
	v_add_u32_e32 v15, 0x2000, v15
	s_waitcnt lgkmcnt(11)
	v_fma_f32 v27, -v5, v9, v38
	v_fma_f32 v26, v4, v8, v39
	v_fma_f32 v8, v2, v8, v27
	v_fma_f32 v9, v3, v9, v26
	v_add_u32_e32 v14, 0x2000, v14
	v_add_u32_e32 v13, 0x2000, v13
	v_add_u32_e32 v12, 0x2000, v12
	s_waitcnt lgkmcnt(10)
	v_fma_f32 v27, -v5, v9, v40
	v_fma_f32 v26, v4, v8, v41
	v_fma_f32 v8, v2, v8, v27
	v_fma_f32 v9, v3, v9, v26
	v_add_u32_e32 v11, 0x2000, v11
	v_add_u32_e32 v10, 0x2000, v10
	s_cmp_ge_u32 s35, s6
	s_waitcnt lgkmcnt(9)
	v_fma_f32 v27, -v5, v9, v42
	v_fma_f32 v26, v4, v8, v43
	v_fma_f32 v8, v2, v8, v27
	v_fma_f32 v9, v3, v9, v26
	s_nop 0
	s_nop 0
	s_nop 0
	s_waitcnt lgkmcnt(8)
	v_fma_f32 v27, -v5, v9, v44
	v_fma_f32 v26, v4, v8, v45
	v_fma_f32 v8, v2, v8, v27
	v_fma_f32 v9, v3, v9, v26
	s_nop 0
	s_nop 0
	s_nop 0
	s_waitcnt lgkmcnt(7)
	v_fma_f32 v27, -v5, v9, v46
	v_fma_f32 v26, v4, v8, v47
	v_fma_f32 v8, v2, v8, v27
	v_fma_f32 v9, v3, v9, v26
	s_nop 0
	s_nop 0
	s_nop 0
	s_waitcnt lgkmcnt(6)
	v_fma_f32 v27, -v5, v9, v48
	v_fma_f32 v26, v4, v8, v49
	v_fma_f32 v8, v2, v8, v27
	v_fma_f32 v9, v3, v9, v26
	s_nop 0
	s_nop 0
	s_nop 0
	s_waitcnt lgkmcnt(5)
	v_fma_f32 v27, -v5, v9, v50
	v_fma_f32 v26, v4, v8, v51
	v_fma_f32 v8, v2, v8, v27
	v_fma_f32 v9, v3, v9, v26
	s_nop 0
	s_nop 0
	s_nop 0
	s_waitcnt lgkmcnt(4)
	v_fma_f32 v27, -v5, v9, v52
	v_fma_f32 v26, v4, v8, v53
	v_fma_f32 v8, v2, v8, v27
	v_fma_f32 v9, v3, v9, v26
	s_nop 0
	s_nop 0
	s_nop 0
	s_waitcnt lgkmcnt(3)
	v_fma_f32 v27, -v5, v9, v54
	v_fma_f32 v26, v4, v8, v55
	v_fma_f32 v8, v2, v8, v27
	v_fma_f32 v9, v3, v9, v26
	s_nop 0
	s_nop 0
	s_nop 0
	s_waitcnt lgkmcnt(2)
	v_fma_f32 v27, -v5, v9, v56
	v_fma_f32 v26, v4, v8, v57
	v_fma_f32 v8, v2, v8, v27
	v_fma_f32 v9, v3, v9, v26
	s_nop 0
	s_nop 0
	s_nop 0
	s_waitcnt lgkmcnt(1)
	v_fma_f32 v27, -v5, v9, v58
	v_fma_f32 v26, v4, v8, v59
	v_fma_f32 v8, v2, v8, v27
	v_fma_f32 v9, v3, v9, v26
	s_nop 0
	s_nop 0
	s_nop 0
	s_waitcnt lgkmcnt(0)
	v_fma_f32 v27, -v5, v9, v60
	v_fma_f32 v26, v4, v8, v61
	v_fma_f32 v8, v2, v8, v27
	v_fma_f32 v9, v3, v9, v26
	s_cbranch_scc0 .LBB0_281
	s_mov_b64 s[52:53], 0

; #define LAS __attribute__((address_space(3)))
; __device__ __forceinline__ unsigned cvt_pk_bf16(float lo, float hi) { unsigned r; asm volatile("v_cvt_pk_bf16_f32 %0, %1, %2" : "=v"(r) : "v"(lo), "v"(hi)); return r; }
; __device__ __forceinline__ f32x2 cmul(f32x2 a, f32x2 b) { return (f32x2){a.x * b.x - a.y * b.y, a.x * b.y + a.y * b.x}; }
; __global__ void __launch_bounds__(512, 2) fwd_kernel(Args a) {
;     ...
; #pragma unroll
;                 for (int cc = 0; cc < 16; ++cc) {
;                     *(LAS unsigned*)(hl + cc * 136 + 2 * lane) = cvt_pk_bf16(S.x, S.y);
;                     const f32x2 e = *(const LAS f32x2*)(EbB + (c0 + cc) * 512 + ((ch ^ cc) << 4) + wo); S = cmul(aT, S) + e;
;                 }
;                 if (wave == 7) { out[O_PRE + (size_t)nb * 2048 + g * NP + lane] = S.x; out[O_PIM + (size_t)nb * 2048 + g * NP + lane] = S.y; }
.LBB0_285:
	s_waitcnt vmcnt(0)
	v_add_u32_e32 v28, v113, v96
	ds_read_b64 v[36:37], v28
	v_add_u32_e32 v28, v113, v98
	ds_read_b64 v[38:39], v28 offset:512
	v_add_u32_e32 v28, v113, v99
	ds_read_b64 v[40:41], v28 offset:1024
	v_add_u32_e32 v28, v113, v100
	ds_read_b64 v[42:43], v28 offset:1536
	v_add_u32_e32 v28, v113, v101
	ds_read_b64 v[44:45], v28 offset:2048
	v_add_u32_e32 v28, v113, v102
	ds_read_b64 v[46:47], v28 offset:2560
	v_add_u32_e32 v28, v113, v103
	ds_read_b64 v[48:49], v28 offset:3072
	v_add_u32_e32 v28, v113, v104
	ds_read_b64 v[50:51], v28 offset:3584
	v_cvt_pk_bf16_f32 v6, v8, v9
	ds_write_b32 v143, v6
	s_and_b64 vcc, exec, s[10:11]
	s_nop 0
	s_waitcnt lgkmcnt(8)
	v_fma_f32 v11, -v5, v9, v36
	v_fma_f32 v10, v4, v8, v37
	v_fma_f32 v6, v2, v8, v11
	v_fma_f32 v7, v3, v9, v10
	s_nop 0
	v_cvt_pk_bf16_f32 v8, v6, v7
	ds_write_b32 v143, v8 offset:272
	s_nop 0
	s_nop 0
	s_waitcnt lgkmcnt(8)
	v_fma_f32 v11, -v5, v7, v38
	v_fma_f32 v10, v4, v6, v39
	v_fma_f32 v6, v2, v6, v11
	v_fma_f32 v7, v3, v7, v10
	s_nop 0
	v_cvt_pk_bf16_f32 v8, v6, v7
	ds_write_b32 v143, v8 offset:544
	s_nop 0
	s_nop 0
	s_waitcnt lgkmcnt(8)
	v_fma_f32 v11, -v5, v7, v40
	v_fma_f32 v10, v4, v6, v41
	v_fma_f32 v6, v2, v6, v11
	v_fma_f32 v7, v3, v7, v10
	s_nop 0
	v_cvt_pk_bf16_f32 v8, v6, v7
	ds_write_b32 v143, v8 offset:816
	s_nop 0
	s_nop 0
	s_waitcnt lgkmcnt(8)
	v_fma_f32 v11, -v5, v7, v42
	v_fma_f32 v10, v4, v6, v43
	v_fma_f32 v6, v2, v6, v11
	v_fma_f32 v7, v3, v7, v10
	s_nop 0
	v_cvt_pk_bf16_f32 v8, v6, v7
	ds_write_b32 v143, v8 offset:1088
	s_nop 0
	s_nop 0
	s_waitcnt lgkmcnt(8)
	v_fma_f32 v11, -v5, v7, v44
	v_fma_f32 v10, v4, v6, v45
	v_fma_f32 v6, v2, v6, v11
	v_fma_f32 v7, v3, v7, v10
	s_nop 0
	v_cvt_pk_bf16_f32 v8, v6, v7
	ds_write_b32 v143, v8 offset:1360
	s_nop 0
	s_nop 0
	s_waitcnt lgkmcnt(8)
	v_fma_f32 v11, -v5, v7, v46
	v_fma_f32 v10, v4, v6, v47
	v_fma_f32 v6, v2, v6, v11
	v_fma_f32 v7, v3, v7, v10
	s_nop 0
	v_cvt_pk_bf16_f32 v8, v6, v7
	ds_write_b32 v143, v8 offset:1632
	s_nop 0
	s_nop 0
	s_waitcnt lgkmcnt(8)
	v_fma_f32 v11, -v5, v7, v48
	v_fma_f32 v10, v4, v6, v49
	v_fma_f32 v6, v2, v6, v11
	v_fma_f32 v7, v3, v7, v10
	s_nop 0
	v_cvt_pk_bf16_f32 v8, v6, v7
	ds_write_b32 v143, v8 offset:1904
	s_nop 0
	s_nop 0
	s_waitcnt lgkmcnt(8)
	v_fma_f32 v11, -v5, v7, v50
	v_fma_f32 v10, v4, v6, v51
	v_fma_f32 v6, v2, v6, v11
	v_fma_f32 v7, v3, v7, v10
	v_add_u32_e32 v28, v113, v105
	ds_read_b64 v[52:53], v28 offset:4096
	v_add_u32_e32 v28, v113, v106
	ds_read_b64 v[54:55], v28 offset:4608
	v_add_u32_e32 v28, v113, v107
	ds_read_b64 v[56:57], v28 offset:5120
	v_add_u32_e32 v28, v113, v108
	ds_read_b64 v[58:59], v28 offset:5632
	v_add_u32_e32 v28, v113, v109
	ds_read_b64 v[60:61], v28 offset:6144
	v_add_u32_e32 v28, v113, v110
	ds_read_b64 v[62:63], v28 offset:6656
	v_add_u32_e32 v28, v113, v111
	ds_read_b64 v[64:65], v28 offset:7168
	s_nop 0
	v_cvt_pk_bf16_f32 v8, v6, v7
	ds_write_b32 v143, v8 offset:2176
	s_nop 0
	s_nop 0
	s_waitcnt lgkmcnt(7)
	v_fma_f32 v11, -v5, v7, v52
	v_fma_f32 v10, v4, v6, v53
	v_fma_f32 v6, v2, v6, v11
	v_fma_f32 v7, v3, v7, v10
	s_nop 0
	v_cvt_pk_bf16_f32 v8, v6, v7
	ds_write_b32 v143, v8 offset:2448
	s_nop 0
	s_nop 0
	s_waitcnt lgkmcnt(7)
	v_fma_f32 v11, -v5, v7, v54
	v_fma_f32 v10, v4, v6, v55
	v_fma_f32 v6, v2, v6, v11
	v_fma_f32 v7, v3, v7, v10
	s_nop 0
	v_cvt_pk_bf16_f32 v8, v6, v7
	ds_write_b32 v143, v8 offset:2720
	s_nop 0
	s_nop 0
	s_waitcnt lgkmcnt(7)
	v_fma_f32 v11, -v5, v7, v56
	v_fma_f32 v10, v4, v6, v57
	v_fma_f32 v6, v2, v6, v11
	v_fma_f32 v7, v3, v7, v10
	s_nop 0
	v_cvt_pk_bf16_f32 v8, v6, v7
	ds_write_b32 v143, v8 offset:2992
	s_nop 0
	s_nop 0
	s_waitcnt lgkmcnt(7)
	v_fma_f32 v11, -v5, v7, v58
	v_fma_f32 v10, v4, v6, v59
	v_fma_f32 v6, v2, v6, v11
	v_fma_f32 v7, v3, v7, v10
	s_nop 0
	v_cvt_pk_bf16_f32 v8, v6, v7
	ds_write_b32 v143, v8 offset:3264
	s_nop 0
	s_nop 0
	s_waitcnt lgkmcnt(7)
	v_fma_f32 v11, -v5, v7, v60
	v_fma_f32 v10, v4, v6, v61
	v_fma_f32 v6, v2, v6, v11
	v_fma_f32 v7, v3, v7, v10
	s_nop 0
	v_cvt_pk_bf16_f32 v8, v6, v7
	ds_write_b32 v143, v8 offset:3536
	s_nop 0
	s_nop 0
	s_waitcnt lgkmcnt(7)
	v_fma_f32 v11, -v5, v7, v62
	v_fma_f32 v10, v4, v6, v63
	v_fma_f32 v6, v2, v6, v11
	v_fma_f32 v7, v3, v7, v10
	s_nop 0
	v_cvt_pk_bf16_f32 v8, v6, v7
	ds_write_b32 v143, v8 offset:3808
	s_nop 0
	s_nop 0
	s_waitcnt lgkmcnt(7)
	v_fma_f32 v11, -v5, v7, v64
	v_fma_f32 v10, v4, v6, v65
	v_fma_f32 v6, v2, v6, v11
	v_fma_f32 v7, v3, v7, v10
	s_nop 0
	v_cvt_pk_bf16_f32 v8, v6, v7
	ds_write_b32 v143, v8 offset:4080
	s_cbranch_vccz .LBB0_278
	s_ashr_i32 s51, s50, 31
	s_lshl_b32 s35, s34, 13
	s_add_u32 s35, s12, s35
	s_addc_u32 s39, s13, 0
	s_lshl_b64 s[36:37], s[50:51], 2
	v_add_u32_e32 v8, v113, v112
	s_add_u32 s36, s35, s36
	ds_read_b64 v[8:9], v8 offset:7680
	v_pk_mul_f32 v[4:5], v[4:5], v[6:7]
	v_mov_b32_e32 v75, v67
	s_addc_u32 s37, s39, s37
	v_pk_fma_f32 v[10:11], v[2:3], v[6:7], v[4:5] op_sel:[0,0,1] op_sel_hi:[1,1,0] neg_lo:[0,0,1] neg_hi:[0,0,1]
	v_pk_fma_f32 v[2:3], v[2:3], v[6:7], v[4:5] op_sel:[0,0,1] op_sel_hi:[1,1,0]
	v_lshl_add_u64 v[4:5], s[36:37], 0, v[74:75]
	v_add_co_u32_e32 v6, vcc, 0x4080000, v4
	v_mov_b32_e32 v11, v3
	s_nop 0
	v_addc_co_u32_e32 v7, vcc, 0, v5, vcc
	v_add_co_u32_e32 v4, vcc, 0x4090000, v4
	s_waitcnt lgkmcnt(0)
	v_pk_add_f32 v[2:3], v[10:11], v[8:9]
	v_addc_co_u32_e32 v5, vcc, 0, v5, vcc
	global_store_dword v[6:7], v2, off
	global_store_dword v[4:5], v3, off
	s_branch .LBB0_278
